# GDN scan: output norm block rewritten (v_exp/v_rcp/v_rsq f32) and interleaved into MFMA phase; plus 4/4 DMA rebalance in GEMMs
# speedup vs baseline: 1.0065x; 1.0006x over previous
; __device__ __forceinline__ float bflo(unsigned w) { return __uint_as_float(w << 16); }
; __device__ __forceinline__ float bfhi(unsigned w) { return __uint_as_float(w & 0xffff0000u); }
; __device__ __forceinline__ void gdn_scan8(const unsigned char* REC, const bf16* UF, const float* EG, bf16* OA, const bf16* P, const float* norm_w, LAS unsigned char* lds, int bh) {
;     ...
;     for (int n = 0; n < 64; ++n) {
;         if (n > 0) G2_NORM_OUT(n - 1);
;         f32x4 Vn[4], O[4]; const float egc = eg;
;         Vn[0] = (f32x4){bflo(u0.x), bfhi(u0.x), bflo(u0.y), bfhi(u0.y)}; Vn[1] = (f32x4){bflo(u0.z), bfhi(u0.z), bflo(u0.w), bfhi(u0.w)};
;         Vn[2] = (f32x4){bflo(u1.x), bfhi(u1.x), bflo(u1.y), bfhi(u1.y)}; Vn[3] = (f32x4){bflo(u1.z), bfhi(u1.z), bflo(u1.w), bfhi(u1.w)};
;         { const bf16* zq = zp + (size_t)n * 64 * LDP; z0 = *(const v4u*)zq; z1 = *(const v4u*)(zq + (size_t)4 * LDP); }
;         if (n + 1 < 64) { const bf16* up = ufp + (size_t)(n + 1) * (8 * 64 * 16); u0 = *(const v4u*)up; u1 = *(const v4u*)(up + 8); eg = EG[bh * 64 + n + 1]; }
.LBB0_546:
	s_and_b32 s35, 1, s8
	s_cselect_b32 s0, 0x4400, 0
	v_add_u32_e32 v200, s0, v81
	ds_read_b128 v[204:207], v200
	ds_read_b128 v[208:211], v200 offset:1088
	v_lshl_add_u64 v[202:203], s[64:65], 0, v[100:101]
	s_nop 0
	v_add_co_u32_e32 v252, vcc, s31, v202
	s_nop 1
	v_addc_co_u32_e32 v253, vcc, 0, v203, vcc
	v_add_co_u32_e32 v246, vcc, s34, v202
	s_nop 1
	v_addc_co_u32_e32 v247, vcc, 0, v203, vcc
	v_lshlrev_b32_e32 v212, 16, v14
	v_and_b32_e32 v213, 0xffff0000, v14
	v_lshlrev_b32_e32 v214, 16, v15
	v_and_b32_e32 v215, 0xffff0000, v15
	v_lshlrev_b32_e32 v216, 16, v16
	v_and_b32_e32 v217, 0xffff0000, v16
	v_lshlrev_b32_e32 v218, 16, v17
	v_and_b32_e32 v219, 0xffff0000, v17
	v_lshlrev_b32_e32 v220, 16, v10
	v_and_b32_e32 v221, 0xffff0000, v10
	v_lshlrev_b32_e32 v222, 16, v11
	v_and_b32_e32 v223, 0xffff0000, v11
	v_lshlrev_b32_e32 v224, 16, v12
	v_and_b32_e32 v225, 0xffff0000, v12
	v_lshlrev_b32_e32 v226, 16, v13
	v_and_b32_e32 v227, 0xffff0000, v13
	s_cmp_lg_u32 s10, 0x364000
	s_cselect_b64 s[0:1], -1, 0
	s_cmp_eq_u32 s10, 0x364000
	v_lshl_add_u64 v[10:11], s[64:65], 0, v[98:99]
	v_add_co_u32_e32 v12, vcc, 0x27cc3000, v10
	s_nop 1
	v_addc_co_u32_e32 v13, vcc, 0, v11, vcc
	v_add_co_u32_e32 v10, vcc, 0x27cef000, v10
	s_nop 1
	v_addc_co_u32_e32 v11, vcc, 0, v11, vcc
	global_load_dwordx4 v[14:17], v[12:13], off
	s_nop 0
	global_load_dwordx4 v[10:13], v[10:11], off
	s_cbranch_scc1 .LBB0_548
	v_lshl_add_u64 v[34:35], s[64:65], 0, v[74:75]
	v_lshl_add_u64 v[36:37], v[34:35], 0, s[24:25]
	v_add_co_u32_e32 v34, vcc, 0x108000, v34
	s_add_u32 s4, s64, s9
	s_nop 0
	v_addc_co_u32_e32 v35, vcc, 0, v35, vcc
	s_addc_u32 s5, s65, s40
	global_load_dwordx4 v[38:41], v[34:35], off
	s_nop 0
	global_load_dwordx4 v[34:37], v[36:37], off offset:16
	s_nop 0
	global_load_dword v106, v199, s[4:5]

; #define LAS __attribute__((address_space(3)))
; __device__ __forceinline__ float bflo(unsigned w) { return __uint_as_float(w << 16); }
; __device__ __forceinline__ float bfhi(unsigned w) { return __uint_as_float(w & 0xffff0000u); }
; #define GSTAGE(nn, bufi) do { _Pragma("unroll") for (int i_ = 0; i_ < 7; ++i_) { const int p_ = wave + 8 * i_; \
;         __builtin_amdgcn_global_load_lds((const unsigned*)(recb + (size_t)(nn) * GREC + p_ * 1024 + lane * 16), (LAS unsigned*)(lds + (bufi) * GREC + p_ * 1024), 16, 0, 0); } } while (0)
; __device__ __forceinline__ void gdn_scan8(const unsigned char* REC, const bf16* UF, const float* EG, bf16* OA, const bf16* P, const float* norm_w, LAS unsigned char* lds, int bh) {
;     ...
;         Vn[0] = (f32x4){bflo(u0.x), bfhi(u0.x), bflo(u0.y), bfhi(u0.y)}; Vn[1] = (f32x4){bflo(u0.z), bfhi(u0.z), bflo(u0.w), bfhi(u0.w)};
;         Vn[2] = (f32x4){bflo(u1.x), bfhi(u1.x), bflo(u1.y), bfhi(u1.y)}; Vn[3] = (f32x4){bflo(u1.z), bfhi(u1.z), bflo(u1.w), bfhi(u1.w)};
;         { const bf16* zq = zp + (size_t)n * 64 * LDP; z0 = *(const v4u*)zq; z1 = *(const v4u*)(zq + (size_t)4 * LDP); }
;         if (n + 1 < 64) { const bf16* up = ufp + (size_t)(n + 1) * (8 * 64 * 16); u0 = *(const v4u*)up; u1 = *(const v4u*)(up + 8); eg = EG[bh * 64 + n + 1]; }
;         __builtin_amdgcn_sched_barrier(0);
;         if (n + 1 < 64) GSTAGE(n + 1, (n + 1) & 1);
;         __builtin_amdgcn_sched_barrier(0);
;         bf16x8 Sb[4];
; #pragma unroll
;         for (int ks = 0; ks < 4; ++ks) Sb[ks] = pack_b(S[2 * ks], S[2 * ks + 1]);
;         const LAS unsigned char* base = lds + (n & 1) * GREC + lane * 16;
; #pragma unroll
;         for (int ct = 0; ct < 4; ++ct) { O[ct] = (f32x4){0.f, 0.f, 0.f, 0.f};
; #pragma unroll
;             for (int ks = 0; ks < 4; ++ks) {
;                 Vn[ct] = __builtin_amdgcn_mfma_f32_16x16x32_bf16(*(const LAS bf16x8*)(base + GR_W + (ct * 4 + ks) * 1024), Sb[ks], Vn[ct], 0, 0, 0);
;                 O[ct] = __builtin_amdgcn_mfma_f32_16x16x32_bf16(*(const LAS bf16x8*)(base + GR_Q + (ct * 4 + ks) * 1024), Sb[ks], O[ct], 0, 0, 0); } }
.LBB0_550:
	s_add_i32 s8, s8, 1
	v_lshlrev_b32_e32 v66, 16, v22
	v_and_b32_e32 v67, 0xffff0000, v22
	v_lshlrev_b32_e32 v68, 16, v23
	v_and_b32_e32 v69, 0xffff0000, v23
	v_lshlrev_b32_e32 v22, 16, v24
	v_and_b32_e32 v23, 0xffff0000, v24
	v_lshlrev_b32_e32 v24, 16, v25
	v_and_b32_e32 v25, 0xffff0000, v25
	v_lshlrev_b32_e32 v70, 16, v18
	v_and_b32_e32 v71, 0xffff0000, v18
	v_lshlrev_b32_e32 v72, 16, v19
	v_and_b32_e32 v73, 0xffff0000, v19
	v_lshlrev_b32_e32 v18, 16, v20
	v_and_b32_e32 v19, 0xffff0000, v20
	v_lshlrev_b32_e32 v20, 16, v21
	v_and_b32_e32 v21, 0xffff0000, v21
	s_and_b32 s0, s8, 1
	s_mul_i32 s1, s0, 0xe000
	v_add_u32_e32 v102, s1, v77
	ds_read_b128 v[108:111], v102
	ds_read_b128 v[116:119], v102 offset:1024
	v_cvt_pk_bf16_f32 v112, v26, v27
	v_cvt_pk_bf16_f32 v113, v28, v29
	v_cvt_pk_bf16_f32 v114, v30, v31
	v_cvt_pk_bf16_f32 v115, v32, v33
	v_cvt_pk_bf16_f32 v120, v42, v43
	v_cvt_pk_bf16_f32 v121, v44, v45
	v_cvt_pk_bf16_f32 v122, v46, v47
	v_mul_f32_e32 v201, 0xbfb8aa3b, v212
	v_mul_f32_e32 v202, 0xbfb8aa3b, v213
	v_exp_f32_e32 v201, v201
	s_waitcnt lgkmcnt(0)
	v_exp_f32_e32 v202, v202
	v_add_f32_e32 v201, 1.0, v201
	v_add_f32_e32 v202, 1.0, v202
	v_mfma_f32_16x16x32_bf16 v[66:69], v[108:111], v[112:115], v[66:69]
	ds_read_b128 v[108:111], v102 offset:16384
	ds_read_b128 v[124:127], v102 offset:17408
	v_cvt_pk_bf16_f32 v123, v48, v49
	v_cvt_pk_bf16_f32 v128, v50, v51
	v_cvt_pk_bf16_f32 v129, v52, v53
	v_rcp_f32_e32 v201, v201
	v_rcp_f32_e32 v202, v202
	v_mul_f32_e32 v212, v212, v201
	v_mfma_f32_16x16x32_bf16 v[66:69], v[116:119], v[120:123], v[66:69]
	ds_read_b128 v[116:119], v102 offset:2048
	v_cvt_pk_bf16_f32 v130, v54, v55
	v_cvt_pk_bf16_f32 v131, v56, v57
	v_mul_f32_e32 v213, v213, v202
	v_mul_f32_e32 v201, 0xbfb8aa3b, v214
	v_mul_f32_e32 v202, 0xbfb8aa3b, v215
	s_waitcnt lgkmcnt(0)
	v_exp_f32_e32 v201, v201
	v_exp_f32_e32 v202, v202
	v_add_f32_e32 v201, 1.0, v201
	v_mfma_f32_16x16x32_bf16 v[108:111], v[108:111], v[112:115], 0
	v_cvt_pk_bf16_f32 v132, v58, v59
	v_cvt_pk_bf16_f32 v133, v60, v61
	ds_read_b128 v[136:139], v102 offset:19456
	v_add_f32_e32 v202, 1.0, v202
	v_rcp_f32_e32 v201, v201
	v_rcp_f32_e32 v202, v202
	v_mfma_f32_16x16x32_bf16 v[108:111], v[124:127], v[120:123], v[108:111]
	ds_read_b128 v[124:127], v102 offset:3072
	v_cvt_pk_bf16_f32 v134, v62, v63
	v_cvt_pk_bf16_f32 v135, v64, v65
	v_mul_f32_e32 v214, v214, v201
	v_mul_f32_e32 v215, v215, v202
	v_mul_f32_e32 v201, 0xbfb8aa3b, v216
	v_mfma_f32_16x16x32_bf16 v[66:69], v[116:119], v[128:131], v[66:69]
	ds_read_b128 v[116:119], v102 offset:18432
	s_mulk_i32 s0, 0x4400
	v_pk_mul_f32 v[28:29], v[28:29], v[80:81] op_sel_hi:[1,0]
	v_mul_f32_e32 v202, 0xbfb8aa3b, v217
	v_exp_f32_e32 v201, v201
	v_exp_f32_e32 v202, v202
	s_waitcnt lgkmcnt(0)
	v_add_f32_e32 v201, 1.0, v201
	v_add_f32_e32 v202, 1.0, v202
	v_rcp_f32_e32 v201, v201
	v_mfma_f32_16x16x32_bf16 v[108:111], v[116:119], v[128:131], v[108:111]
	v_mul_f32_e64 v26, v26, v80
	v_mul_f32_e64 v27, v27, v80
	v_pk_mul_f32 v[32:33], v[32:33], v[80:81] op_sel_hi:[1,0]
	v_pk_mul_f32 v[30:31], v[30:31], v[80:81] op_sel_hi:[1,0]
	v_rcp_f32_e32 v202, v202
	v_mul_f32_e32 v216, v216, v201
	v_mul_f32_e32 v217, v217, v202
	v_mfma_f32_16x16x32_bf16 v[66:69], v[124:127], v[132:135], v[66:69]
	ds_read_b128 v[116:119], v102 offset:4096
	ds_read_b128 v[124:127], v102 offset:5120
	v_pk_mul_f32 v[44:45], v[44:45], v[80:81] op_sel_hi:[1,0]
	v_pk_mul_f32 v[42:43], v[42:43], v[80:81] op_sel_hi:[1,0]
	v_mul_f32_e32 v201, 0xbfb8aa3b, v218
	v_mul_f32_e32 v202, 0xbfb8aa3b, v219
	v_exp_f32_e32 v201, v201
	v_mfma_f32_16x16x32_bf16 v[108:111], v[136:139], v[132:135], v[108:111]
	s_nop 2
	v_cvt_pk_bf16_f32 v66, v66, v67
	v_cvt_pk_bf16_f32 v67, v68, v69
	v_pk_mul_f32 v[48:49], v[48:49], v[80:81] op_sel_hi:[1,0]
	v_exp_f32_e32 v202, v202
	v_add_f32_e32 v201, 1.0, v201
	v_add_f32_e32 v202, 1.0, v202
	s_waitcnt lgkmcnt(0)
	v_rcp_f32_e32 v201, v201
	v_rcp_f32_e32 v202, v202
	v_mul_f32_e32 v218, v218, v201
	v_mfma_f32_16x16x32_bf16 v[22:25], v[116:119], v[112:115], v[22:25]
	ds_read_b128 v[116:119], v102 offset:20480
	ds_read_b128 v[136:139], v102 offset:21504
	v_pk_mul_f32 v[46:47], v[46:47], v[80:81] op_sel_hi:[1,0]
	v_pk_mul_f32 v[52:53], v[52:53], v[80:81] op_sel_hi:[1,0]
	v_mul_f32_e32 v219, v219, v202
	v_mul_f32_e32 v201, 0xbfb8aa3b, v220
	v_mul_f32_e32 v202, 0xbfb8aa3b, v221
	s_waitcnt lgkmcnt(0)
	v_exp_f32_e32 v201, v201
	v_exp_f32_e32 v202, v202
	v_add_f32_e32 v201, 1.0, v201
	v_mfma_f32_16x16x32_bf16 v[116:119], v[116:119], v[112:115], 0
	v_mul_f32_e64 v50, v50, v80
	v_mul_f32_e64 v51, v51, v80
	v_pk_mul_f32 v[56:57], v[56:57], v[80:81] op_sel_hi:[1,0]
	v_pk_mul_f32 v[54:55], v[54:55], v[80:81] op_sel_hi:[1,0]
	v_add_f32_e32 v202, 1.0, v202
	v_rcp_f32_e32 v201, v201
	v_rcp_f32_e32 v202, v202
	v_mfma_f32_16x16x32_bf16 v[22:25], v[124:127], v[120:123], v[22:25]
	v_mul_f32_e64 v60, v60, v80
	v_mul_f32_e64 v61, v61, v80
	v_pk_mul_f32 v[58:59], v[58:59], v[80:81] op_sel_hi:[1,0]
	v_pk_mul_f32 v[64:65], v[64:65], v[80:81] op_sel_hi:[1,0]
	v_mul_f32_e32 v220, v220, v201
	v_mul_f32_e32 v221, v221, v202
	v_mul_f32_e32 v201, 0xbfb8aa3b, v222
	v_mfma_f32_16x16x32_bf16 v[116:119], v[136:139], v[120:123], v[116:119]
	ds_read_b128 v[124:127], v102 offset:6144
	ds_read_b128 v[136:139], v102 offset:7168
	v_pk_mul_f32 v[62:63], v[62:63], v[80:81] op_sel_hi:[1,0]
	v_add_u32_e32 v80, s0, v79
	v_mul_f32_e32 v202, 0xbfb8aa3b, v223
	v_exp_f32_e32 v201, v201
	v_exp_f32_e32 v202, v202
	s_waitcnt lgkmcnt(0)
; #define LAS __attribute__((address_space(3)))
; __device__ __forceinline__ void gdn_scan8(const unsigned char* REC, const bf16* UF, const float* EG, bf16* OA, const bf16* P, const float* norm_w, LAS unsigned char* lds, int bh) {
;     ...
;         for (int ct = 0; ct < 4; ++ct) { O[ct] = (f32x4){0.f, 0.f, 0.f, 0.f};
; #pragma unroll
;             for (int ks = 0; ks < 4; ++ks) {
;                 Vn[ct] = __builtin_amdgcn_mfma_f32_16x16x32_bf16(*(const LAS bf16x8*)(base + GR_W + (ct * 4 + ks) * 1024), Sb[ks], Vn[ct], 0, 0, 0);
;                 O[ct] = __builtin_amdgcn_mfma_f32_16x16x32_bf16(*(const LAS bf16x8*)(base + GR_Q + (ct * 4 + ks) * 1024), Sb[ks], O[ct], 0, 0, 0); } }
;         bf16x8 Vb[2];
;         Vb[0] = pack_b(Vn[0], Vn[1]); Vb[1] = pack_b(Vn[2], Vn[3]);
	v_add_f32_e32 v201, 1.0, v201
	v_add_f32_e32 v202, 1.0, v202
	v_rcp_f32_e32 v201, v201
	v_mfma_f32_16x16x32_bf16 v[22:25], v[124:127], v[128:131], v[22:25]
	ds_read_b128 v[124:127], v102 offset:22528
	ds_read_b128 v[140:143], v102 offset:23552
	s_add_u32 s9, s9, 4
	s_addc_u32 s40, s40, 0
	v_rcp_f32_e32 v202, v202
	v_mul_f32_e32 v222, v222, v201
	v_mul_f32_e32 v223, v223, v202
	s_waitcnt lgkmcnt(0)
	v_mul_f32_e32 v201, 0xbfb8aa3b, v224
	v_mul_f32_e32 v202, 0xbfb8aa3b, v225
	v_exp_f32_e32 v201, v201
	v_mfma_f32_16x16x32_bf16 v[116:119], v[124:127], v[128:131], v[116:119]
	s_add_u32 s10, s10, 0xe000
	s_addc_u32 s11, s11, 0
	v_lshl_add_u64 v[74:75], v[74:75], 0, s[14:15]
	v_exp_f32_e32 v202, v202
	v_add_f32_e32 v201, 1.0, v201
	v_add_f32_e32 v202, 1.0, v202
	v_mfma_f32_16x16x32_bf16 v[22:25], v[136:139], v[132:135], v[22:25]
	ds_read_b128 v[124:127], v102 offset:8192
	ds_read_b128 v[136:139], v102 offset:9216
	v_lshl_add_u64 v[98:99], v[98:99], 0, s[26:27]
	v_lshl_add_u64 v[100:101], v[100:101], 0, s[28:29]
	v_rcp_f32_e32 v201, v201
	v_rcp_f32_e32 v202, v202
	v_mul_f32_e32 v224, v224, v201
	v_mfma_f32_16x16x32_bf16 v[116:119], v[140:143], v[132:135], v[116:119]
	s_nop 2
	v_cvt_pk_bf16_f32 v68, v22, v23
	v_cvt_pk_bf16_f32 v69, v24, v25
	s_cmp_lg_u32 s10, 0x372000
	v_mul_f32_e32 v225, v225, v202
	v_mul_f32_e32 v201, 0xbfb8aa3b, v226
	v_mul_f32_e32 v202, 0xbfb8aa3b, v227
	s_waitcnt lgkmcnt(0)
	v_exp_f32_e32 v201, v201
	v_exp_f32_e32 v202, v202
	v_add_f32_e32 v201, 1.0, v201
	v_mfma_f32_16x16x32_bf16 v[70:73], v[124:127], v[112:115], v[70:73]
	ds_read_b128 v[124:127], v102 offset:24576
	ds_read_b128 v[140:143], v102 offset:25600
	v_add_f32_e32 v202, 1.0, v202
	v_rcp_f32_e32 v201, v201
	v_rcp_f32_e32 v202, v202
	s_waitcnt lgkmcnt(0)
	v_mul_f32_e32 v226, v226, v201
	v_mul_f32_e32 v227, v227, v202
	s_waitcnt lgkmcnt(0)
	v_mfma_f32_16x16x32_bf16 v[124:127], v[124:127], v[112:115], 0
	v_lshlrev_b32_e32 v228, 16, v204
	v_and_b32_e32 v229, 0xffff0000, v204
	v_lshlrev_b32_e32 v230, 16, v205
	v_mfma_f32_16x16x32_bf16 v[70:73], v[136:139], v[120:123], v[70:73]
	v_and_b32_e32 v231, 0xffff0000, v205
	v_lshlrev_b32_e32 v232, 16, v206
	v_and_b32_e32 v233, 0xffff0000, v206
	v_mfma_f32_16x16x32_bf16 v[124:127], v[140:143], v[120:123], v[124:127]
	ds_read_b128 v[136:139], v102 offset:10240
	ds_read_b128 v[140:143], v102 offset:11264
	v_lshlrev_b32_e32 v234, 16, v207
	v_and_b32_e32 v235, 0xffff0000, v207
	v_lshlrev_b32_e32 v236, 16, v208
	s_waitcnt lgkmcnt(0)
	v_and_b32_e32 v237, 0xffff0000, v208
	v_lshlrev_b32_e32 v238, 16, v209
	v_and_b32_e32 v239, 0xffff0000, v209
	v_mfma_f32_16x16x32_bf16 v[70:73], v[136:139], v[128:131], v[70:73]
	ds_read_b128 v[136:139], v102 offset:26624
	ds_read_b128 v[144:147], v102 offset:27648
	v_lshlrev_b32_e32 v240, 16, v210
	v_and_b32_e32 v241, 0xffff0000, v210
	v_lshlrev_b32_e32 v242, 16, v211
	s_waitcnt lgkmcnt(0)
	v_and_b32_e32 v243, 0xffff0000, v211
	v_mul_f32_e32 v244, v228, v228
	v_fmac_f32_e32 v244, v229, v229
	v_mfma_f32_16x16x32_bf16 v[124:127], v[136:139], v[128:131], v[124:127]
	v_fmac_f32_e32 v244, v230, v230
	v_fmac_f32_e32 v244, v231, v231
	v_fmac_f32_e32 v244, v232, v232
	v_mfma_f32_16x16x32_bf16 v[70:73], v[140:143], v[132:135], v[70:73]
	ds_read_b128 v[136:139], v102 offset:12288
	ds_read_b128 v[140:143], v102 offset:13312
	v_fmac_f32_e32 v244, v233, v233
	v_fmac_f32_e32 v244, v234, v234
	v_fmac_f32_e32 v244, v235, v235
	v_mfma_f32_16x16x32_bf16 v[124:127], v[144:147], v[132:135], v[124:127]
	s_nop 4
	v_cvt_pk_bf16_f32 v22, v70, v71
	v_cvt_pk_bf16_f32 v23, v72, v73
	v_mul_f32_e32 v245, v236, v236
	v_fmac_f32_e32 v245, v237, v237
	v_fmac_f32_e32 v245, v238, v238
	s_waitcnt lgkmcnt(0)
	v_fmac_f32_e32 v245, v239, v239
	v_fmac_f32_e32 v245, v240, v240
	v_fmac_f32_e32 v245, v241, v241
	v_mfma_f32_16x16x32_bf16 v[18:21], v[136:139], v[112:115], v[18:21]
	ds_read_b128 v[136:139], v102 offset:28672
	ds_read_b128 v[144:147], v102 offset:29696
	v_fmac_f32_e32 v245, v242, v242
	v_fmac_f32_e32 v245, v243, v243
	s_nop 1
	s_waitcnt lgkmcnt(0)
	v_add_f32_dpp v244, v244, v244 quad_perm:[1,0,3,2] row_mask:0xf bank_mask:0xf bound_ctrl:1
	v_add_f32_dpp v245, v245, v245 quad_perm:[1,0,3,2] row_mask:0xf bank_mask:0xf bound_ctrl:1
	s_nop 0
	v_mfma_f32_16x16x32_bf16 v[112:115], v[136:139], v[112:115], 0
	ds_read_b128 v[136:139], v102 offset:14336
	ds_read_b128 v[148:151], v102 offset:15360
	v_add_f32_dpp v244, v244, v244 quad_perm:[2,3,0,1] row_mask:0xf bank_mask:0xf bound_ctrl:1
	v_add_f32_dpp v245, v245, v245 quad_perm:[2,3,0,1] row_mask:0xf bank_mask:0xf bound_ctrl:1
	s_nop 0
	v_mfma_f32_16x16x32_bf16 v[18:21], v[140:143], v[120:123], v[18:21]
	ds_read_b128 v[140:143], v102 offset:30720
	ds_read_b128 v[152:155], v102 offset:31744
	v_add_f32_dpp v244, v244, v244 row_half_mirror row_mask:0xf bank_mask:0xf bound_ctrl:1
	v_add_f32_dpp v245, v245, v245 row_half_mirror row_mask:0xf bank_mask:0xf bound_ctrl:1
	s_nop 0
	s_waitcnt lgkmcnt(0)
	v_add_f32_dpp v244, v244, v244 row_mirror row_mask:0xf bank_mask:0xf bound_ctrl:1
	v_add_f32_dpp v245, v245, v245 row_mirror row_mask:0xf bank_mask:0xf bound_ctrl:1
	s_nop 0
	v_mfma_f32_16x16x32_bf16 v[18:21], v[136:139], v[128:131], v[18:21]
	v_fmamk_f32 v244, v244, 0x3c000000, v104
	v_fmamk_f32 v245, v245, 0x3c000000, v104
	v_rsq_f32_e32 v244, v244
	v_mfma_f32_16x16x32_bf16 v[18:21], v[148:151], v[132:135], v[18:21]
	v_rsq_f32_e32 v245, v245
	s_nop 0
	v_mul_f32_e32 v228, v228, v244
	v_mfma_f32_16x16x32_bf16 v[70:73], v[144:147], v[120:123], v[112:115]
	v_mul_f32_e32 v229, v229, v244
	v_mul_f32_e32 v230, v230, v244
	v_mul_f32_e32 v231, v231, v244
	v_mfma_f32_16x16x32_bf16 v[70:73], v[140:143], v[128:131], v[70:73]
	s_nop 5
	v_cvt_pk_bf16_f32 v24, v18, v19
	v_cvt_pk_bf16_f32 v25, v20, v21
	ds_read_b128 v[18:21], v102 offset:49152
	ds_read_b128 v[112:115], v102 offset:50176
	v_mul_f32_e32 v232, v232, v244
	v_mul_f32_e32 v233, v233, v244
	v_mul_f32_e32 v234, v234, v244
	s_waitcnt lgkmcnt(0)
; #define LAS __attribute__((address_space(3)))
; __device__ __forceinline__ unsigned f2bf(float f) { return pk2(f, f) & 0xffffu; }
; __device__ __forceinline__ void gdn_scan8(const unsigned char* REC, const bf16* UF, const float* EG, bf16* OA, const bf16* P, const float* norm_w, LAS unsigned char* lds, int bh) {
;     ...
;         Vb[0] = pack_b(Vn[0], Vn[1]); Vb[1] = pack_b(Vn[2], Vn[3]);
; #pragma unroll
;         for (int ct = 0; ct < 4; ++ct)
; #pragma unroll
;             for (int ks = 0; ks < 2; ++ks) O[ct] = __builtin_amdgcn_mfma_f32_16x16x32_bf16(*(const LAS bf16x8*)(base + GR_QK + (ct * 2 + ks) * 1024), Vb[ks], O[ct], 0, 0, 0);
; #pragma unroll
;         for (int dt = 0; dt < 8; ++dt) { S[dt] = S[dt] * egc;
; #pragma unroll
;             for (int ks = 0; ks < 2; ++ks) S[dt] = __builtin_amdgcn_mfma_f32_16x16x32_bf16(*(const LAS bf16x8*)(base + GR_K + (dt * 2 + ks) * 1024), Vb[ks], S[dt], 0, 0, 0); }
;         { LAS unsigned char* ow = lds + G2_OB + (n & 1) * (64 * G2_OBP) + (4 * fq) * G2_OBP + (16 * wave + fr) * 2;
; #pragma unroll
;           for (int ct = 0; ct < 4; ++ct)
; #pragma unroll
;               for (int r = 0; r < 4; ++r) *(LAS bf16*)(ow + (16 * ct + r) * G2_OBP) = (bf16)f2bf(O[ct][r]); }
;         asm volatile("s_waitcnt vmcnt(0)" ::: "memory");
;         __syncthreads();
;     }
	v_mul_f32_e32 v235, v235, v244
	v_mul_f32_e32 v228, v228, v6
	v_mul_f32_e32 v229, v229, v7
	v_mfma_f32_16x16x32_bf16 v[18:21], v[18:21], v[66:69], v[108:111]
	ds_read_b128 v[120:123], v102 offset:51200
	ds_read_b128 v[128:131], v102 offset:52224
	ds_read_b128 v[136:139], v102 offset:53248
	ds_read_b128 v[140:143], v102 offset:54272
	v_mul_f32_e32 v230, v230, v8
	v_mul_f32_e32 v231, v231, v9
	v_mul_f32_e32 v232, v232, v2
	v_mfma_f32_16x16x32_bf16 v[70:73], v[152:155], v[132:135], v[70:73]
	ds_read_b128 v[132:135], v102 offset:55296
	ds_read_b128 v[144:147], v102 offset:56320
	ds_read_b128 v[108:111], v102 offset:32768
	ds_read_b128 v[148:151], v102 offset:33792
	v_mul_f32_e32 v233, v233, v3
	v_mul_f32_e32 v234, v234, v4
	v_mul_f32_e32 v235, v235, v5
	v_mfma_f32_16x16x32_bf16 v[18:21], v[112:115], v[22:25], v[18:21]
	ds_read_b128 v[112:115], v102 offset:34816
	ds_read_b128 v[152:155], v102 offset:35840
	v_mul_f32_e32 v228, v228, v212
	v_mul_f32_e32 v229, v229, v213
	v_mul_f32_e32 v230, v230, v214
	s_waitcnt lgkmcnt(0)
	v_mul_f32_e32 v231, v231, v215
	v_mul_f32_e32 v232, v232, v216
	v_mul_f32_e32 v233, v233, v217
	v_mfma_f32_16x16x32_bf16 v[116:119], v[120:123], v[66:69], v[116:119]
	s_nop 3
	v_cvt_pk_bf16_f32 v18, v18, s0
	ds_read_b128 v[120:123], v102 offset:36864
	ds_read_b128 v[156:159], v102 offset:37888
	v_mul_f32_e32 v234, v234, v218
	v_mul_f32_e32 v235, v235, v219
	v_cvt_pk_bf16_f32 v248, v228, v229
	v_mfma_f32_16x16x32_bf16 v[124:127], v[136:139], v[66:69], v[124:127]
	v_cvt_pk_bf16_f32 v249, v230, v231
	v_cvt_pk_bf16_f32 v250, v232, v233
	v_cvt_pk_bf16_f32 v251, v234, v235
	v_mfma_f32_16x16x32_bf16 v[70:73], v[132:135], v[66:69], v[70:73]
	global_store_dwordx4 v[252:253], v[248:251], off
	v_mul_f32_e32 v236, v236, v245
	v_mul_f32_e32 v237, v237, v245
	v_mfma_f32_16x16x32_bf16 v[116:119], v[128:131], v[22:25], v[116:119]
	ds_read_b128 v[128:131], v102 offset:38912
	ds_read_b128 v[160:163], v102 offset:39936
	ds_read_b128 v[136:139], v102 offset:40960
	ds_read_b128 v[164:167], v102 offset:41984
	v_mul_f32_e32 v238, v238, v245
	v_mul_f32_e32 v239, v239, v245
	v_mul_f32_e32 v240, v240, v245
	v_mfma_f32_16x16x32_bf16 v[124:127], v[140:143], v[22:25], v[124:127]
	ds_read_b128 v[140:143], v102 offset:43008
	ds_read_b128 v[168:171], v102 offset:44032
	ds_read_b128 v[132:135], v102 offset:45056
	ds_read_b128 v[172:175], v102 offset:46080
	v_mul_f32_e32 v241, v241, v245
	v_mul_f32_e32 v242, v242, v245
	v_mul_f32_e32 v243, v243, v245
	v_mfma_f32_16x16x32_bf16 v[70:73], v[144:147], v[22:25], v[70:73]
	ds_read_b128 v[144:147], v102 offset:47104
	ds_read_b128 v[176:179], v102 offset:48128
	ds_write_b16 v80, v18
	v_cvt_pk_bf16_f32 v18, v19, s0
	ds_write_b16 v80, v18 offset:272
	v_cvt_pk_bf16_f32 v18, v20, s0
	ds_write_b16 v80, v18 offset:544
	v_cvt_pk_bf16_f32 v18, v21, s0
	ds_write_b16 v80, v18 offset:816
	v_cvt_pk_bf16_f32 v18, v116, s0
	ds_write_b16 v80, v18 offset:4352
	v_mul_f32_e32 v236, v236, v6
	v_mul_f32_e32 v237, v237, v7
	v_mul_f32_e32 v238, v238, v8
	s_waitcnt lgkmcnt(0)
	v_mul_f32_e32 v239, v239, v9
	v_mul_f32_e32 v240, v240, v2
	v_mul_f32_e32 v241, v241, v3
	v_mfma_f32_16x16x32_bf16 v[18:21], v[120:123], v[66:69], v[42:45]
	v_cvt_pk_bf16_f32 v102, v118, s0
	v_cvt_pk_bf16_f32 v70, v70, s0
	ds_write_b16 v80, v102 offset:4896
	v_cvt_pk_bf16_f32 v42, v117, s0
	ds_write_b16 v80, v42 offset:4624
	v_mul_f32_e32 v242, v242, v4
	v_mul_f32_e32 v243, v243, v5
	v_mul_f32_e32 v236, v236, v220
	v_mfma_f32_16x16x32_bf16 v[42:45], v[156:159], v[22:25], v[18:21]
	v_cvt_pk_bf16_f32 v102, v125, s0
	ds_write_b16 v80, v70 offset:13056
	v_cvt_pk_bf16_f32 v70, v73, s0
	v_cvt_pk_bf16_f32 v18, v119, s0
	ds_write_b16 v80, v18 offset:5168
	v_mul_f32_e32 v237, v237, v221
	v_mul_f32_e32 v238, v238, v222
	v_mul_f32_e32 v239, v239, v223
	v_mfma_f32_16x16x32_bf16 v[18:21], v[128:131], v[66:69], v[46:49]
	ds_write_b16 v80, v102 offset:8976
	ds_write_b16 v80, v70 offset:13872
	s_nop 0
	v_cvt_pk_bf16_f32 v46, v124, s0
	ds_write_b16 v80, v46 offset:8704
	v_mul_f32_e32 v240, v240, v224
	v_mul_f32_e32 v241, v241, v225
	v_mul_f32_e32 v242, v242, v226
	v_mfma_f32_16x16x32_bf16 v[46:49], v[160:163], v[22:25], v[18:21]
	s_nop 2
	v_cvt_pk_bf16_f32 v18, v126, s0
	ds_write_b16 v80, v18 offset:9248
	v_mul_f32_e32 v243, v243, v227
	v_cvt_pk_bf16_f32 v204, v236, v237
	v_cvt_pk_bf16_f32 v205, v238, v239
	v_mfma_f32_16x16x32_bf16 v[18:21], v[136:139], v[66:69], v[50:53]
	s_nop 2
	v_cvt_pk_bf16_f32 v50, v127, s0
	ds_write_b16 v80, v50 offset:9520
	v_cvt_pk_bf16_f32 v206, v240, v241
	v_cvt_pk_bf16_f32 v207, v242, v243
	global_store_dwordx4 v[246:247], v[204:207], off
	v_mfma_f32_16x16x32_bf16 v[50:53], v[164:167], v[22:25], v[18:21]
	s_nop 2
	v_cvt_pk_bf16_f32 v18, v71, s0
	ds_write_b16 v80, v18 offset:13328
	v_mfma_f32_16x16x32_bf16 v[18:21], v[140:143], v[66:69], v[54:57]
	s_nop 2
	v_cvt_pk_bf16_f32 v54, v72, s0
	ds_write_b16 v80, v54 offset:13600
	v_mfma_f32_16x16x32_bf16 v[54:57], v[168:171], v[22:25], v[18:21]
	s_waitcnt vmcnt(0)
	s_waitcnt vmcnt(0) lgkmcnt(0)
	s_barrier
	v_mfma_f32_16x16x32_bf16 v[18:21], v[132:135], v[66:69], v[58:61]
	v_mfma_f32_16x16x32_bf16 v[26:29], v[108:111], v[66:69], v[26:29]
	v_mfma_f32_16x16x32_bf16 v[30:33], v[112:115], v[66:69], v[30:33]
	v_mfma_f32_16x16x32_bf16 v[58:61], v[172:175], v[22:25], v[18:21]
	v_mfma_f32_16x16x32_bf16 v[18:21], v[144:147], v[66:69], v[62:65]
	v_mfma_f32_16x16x32_bf16 v[26:29], v[148:151], v[22:25], v[26:29]
	v_mfma_f32_16x16x32_bf16 v[30:33], v[152:155], v[22:25], v[30:33]
	v_mfma_f32_16x16x32_bf16 v[62:65], v[176:179], v[22:25], v[18:21]
	s_cbranch_scc0 .LBB0_552
	v_mov_b64_e32 v[22:23], v[38:39]
	s_nop 2
	v_mov_b64_e32 v[18:19], v[34:35]
	v_mov_b64_e32 v[24:25], v[40:41]
	v_mov_b64_e32 v[20:21], v[36:37]
	v_mov_b32_e32 v80, v106
	s_branch .LBB0_546
